# feat_c channel-DFT fold: the 8 tasks of a wave issue all 32 loads up front and retire behind counted waits (was one load round trip per task)
# speedup vs baseline: 1.0083x; 1.0004x over previous
; DI unsigned cvtpk(float lo, float hi) { f32x2 v = {lo, hi}; bf16x2_t b = __builtin_convertvector(v, bf16x2_t); return __builtin_bit_cast(unsigned, b); }
; DI float bflo(unsigned u) { return __uint_as_float(u << 16); }
; DI float bfhi(unsigned u) { return __uint_as_float(u & 0xffff0000u); }
; DI void phase_feat_c(KP p, int l) {
;     ...
;   {
;     const bf16_t* FT = (const bf16_t*)(ws + WS_FT); bf16_t* FTF = (bf16_t*)(ws + WS_FTF);
;     for (int task = gw; task < NB * 256 * 4; task += nw) {
;       const int row = task >> 2, k8 = (task & 3) * 512 + lane * 8;
;       const bf16_t* fr = FT + (size_t)row * 4096;
;       const bool cosp = k8 < 1024;
;       const int f0 = cosp ? k8 : 2048 + (k8 - 1024);
;       const int mi = cosp ? 2048 - k8 : 4096 - (k8 - 1024);
;       const u32x4 fw = *(const u32x4*)(fr + f0), ml = *(const u32x4*)(fr + mi - 8);
;       const float m0v = bflo((unsigned)fr[(mi < 4096) ? mi : 4095]);
;       const float f[8] = {bflo(fw.x), bfhi(fw.x), bflo(fw.y), bfhi(fw.y), bflo(fw.z), bfhi(fw.z), bflo(fw.w), bfhi(fw.w)};
;       const float mr[8] = {m0v, bfhi(ml.w), bflo(ml.w), bfhi(ml.z), bflo(ml.z), bfhi(ml.y), bflo(ml.y), bfhi(ml.x)};
;       float v[8];
; #pragma unroll
;       for (int e = 0; e < 8; ++e) {
;         const int k = k8 + e;
;         if (k < 1024) v[e] = f[e] + ((k == 0) ? 0.f : mr[e]);
;         else if (k == 1024) v[e] = bflo((unsigned)fr[1024]);
;         else v[e] = f[e] - mr[e];
;       }
;       u32x4 o = {cvtpk(v[0], v[1]), cvtpk(v[2], v[3]), cvtpk(v[4], v[5]), cvtpk(v[6], v[7])};
;       *(u32x4*)(FTF + (size_t)row * 2048 + k8) = o;
;     }
.LBB0_182:
	s_and_b64 vcc, exec, s[4:5]
	s_cbranch_vccz .LBB0_214
	s_load_dwordx2 s[4:5], s[0:1], 0xb8
	v_mov_b32_e32 v15, v196
	s_waitcnt lgkmcnt(0)
	v_readlane_b32 s2, v253, 6
	v_ashrrev_i32_e32 v26, 6, v15
	v_and_b32_e32 v14, 63, v15
	v_add_u32_e32 v50, s2, v26
	v_cmp_gt_i32_e32 vcc, s12, v50
	s_and_saveexec_b64 s[18:19], vcc
	s_cbranch_execz .LBB0_194
	s_add_u32 s20, s4, 0x11b75100
	s_addc_u32 s21, s5, 0
	s_add_u32 s36, s4, 0x13b75100
	s_addc_u32 s37, s5, 0
	s_movk_i32 s2, 0x400
	v_and_b32_e32 v35, 3, v50
	v_lshlrev_b32_e32 v34, 3, v14
	v_lshl_or_b32 v34, v35, 9, v34
	v_lshrrev_b32_e32 v39, 2, v50
	v_cmp_gt_u32_e64 s[40:41], s2, v34
	v_cmp_eq_u32_e64 s[34:35], 0, v34
	v_cmp_eq_u32_e64 s[42:43], s2, v34
	v_add_u32_e32 v36, 0x400, v34
	v_sub_u32_e32 v37, 0x800, v34
	v_sub_u32_e32 v38, 0x1400, v34
	v_lshlrev_b32_e32 v45, 13, v39
	v_lshlrev_b32_e32 v46, 12, v39
	v_cndmask_b32_e64 v36, v36, v34, s[40:41]
	v_cndmask_b32_e64 v37, v38, v37, s[40:41]
	v_min_u32_e32 v38, 0xfff, v37
	v_add_u32_e32 v41, -8, v37
	v_lshl_add_u32 v40, v36, 1, v45
	v_lshl_add_u32 v41, v41, 1, v45
	v_lshl_add_u32 v42, v38, 1, v45
	v_add_u32_e32 v43, 0x800, v45
	v_lshl_add_u32 v44, v34, 1, v46
	s_waitcnt vmcnt(0)
	global_load_dwordx4 v[216:219], v40, s[20:21]
	global_load_dwordx4 v[220:223], v41, s[20:21]
	global_load_ushort v224, v42, s[20:21]
	global_load_ushort v225, v43, s[20:21]
	s_add_u32 s52, s20, 0x400000
	s_addc_u32 s53, s21, 0
	global_load_dwordx4 v[226:229], v40, s[52:53]
	global_load_dwordx4 v[230:233], v41, s[52:53]
	global_load_ushort v234, v42, s[52:53]
	global_load_ushort v235, v43, s[52:53]
	s_add_u32 s52, s20, 0x800000
	s_addc_u32 s53, s21, 0
	global_load_dwordx4 v[236:239], v40, s[52:53]
	global_load_dwordx4 v[240:243], v41, s[52:53]
	global_load_ushort v244, v42, s[52:53]
	global_load_ushort v245, v43, s[52:53]
	s_add_u32 s52, s20, 0xc00000
	s_addc_u32 s53, s21, 0
	global_load_dwordx4 v[128:131], v40, s[52:53]
	global_load_dwordx4 v[132:135], v41, s[52:53]
	global_load_ushort v136, v42, s[52:53]
	global_load_ushort v137, v43, s[52:53]
	s_add_u32 s52, s20, 0x1000000
	s_addc_u32 s53, s21, 0
	global_load_dwordx4 v[138:141], v40, s[52:53]
	global_load_dwordx4 v[142:145], v41, s[52:53]
	global_load_ushort v146, v42, s[52:53]
	global_load_ushort v147, v43, s[52:53]
	s_add_u32 s52, s20, 0x1400000
	s_addc_u32 s53, s21, 0
	global_load_dwordx4 v[148:151], v40, s[52:53]
	global_load_dwordx4 v[152:155], v41, s[52:53]
	global_load_ushort v156, v42, s[52:53]
	global_load_ushort v157, v43, s[52:53]
	s_add_u32 s52, s20, 0x1800000
	s_addc_u32 s53, s21, 0
	global_load_dwordx4 v[82:85], v40, s[52:53]
	global_load_dwordx4 v[86:89], v41, s[52:53]
	global_load_ushort v90, v42, s[52:53]
	global_load_ushort v91, v43, s[52:53]
	s_add_u32 s52, s20, 0x1c00000
	s_addc_u32 s53, s21, 0
	global_load_dwordx4 v[92:95], v40, s[52:53]
	global_load_dwordx4 v[96:99], v41, s[52:53]
	global_load_ushort v100, v42, s[52:53]
	global_load_ushort v101, v43, s[52:53]
	s_waitcnt vmcnt(28)
	v_lshlrev_b32_e32 v51, 16, v216
	v_and_b32_e32 v52, 0xffff0000, v216
	v_lshlrev_b32_e32 v53, 16, v217
	v_and_b32_e32 v54, 0xffff0000, v217
	v_lshlrev_b32_e32 v55, 16, v218
	v_and_b32_e32 v56, 0xffff0000, v218
	v_lshlrev_b32_e32 v57, 16, v219
	v_and_b32_e32 v58, 0xffff0000, v219
	v_lshlrev_b32_e32 v59, 16, v224
	v_cndmask_b32_e64 v59, v59, 0, s[34:35]
	v_cndmask_b32_e64 v59, -v59, v59, s[40:41]
	v_add_f32_e32 v51, v59, v51
	v_and_b32_e32 v59, 0xffff0000, v223
	v_cndmask_b32_e64 v59, -v59, v59, s[40:41]
	v_add_f32_e32 v52, v59, v52
	v_lshlrev_b32_e32 v64, 16, v223
	v_cndmask_b32_e64 v64, -v64, v64, s[40:41]
	v_add_f32_e32 v53, v64, v53
	v_and_b32_e32 v59, 0xffff0000, v222
	v_cndmask_b32_e64 v59, -v59, v59, s[40:41]
	v_add_f32_e32 v54, v59, v54
	v_lshlrev_b32_e32 v64, 16, v222
	v_cndmask_b32_e64 v64, -v64, v64, s[40:41]
	v_add_f32_e32 v55, v64, v55
	v_and_b32_e32 v59, 0xffff0000, v221
	v_cndmask_b32_e64 v59, -v59, v59, s[40:41]
	v_add_f32_e32 v56, v59, v56
	v_lshlrev_b32_e32 v64, 16, v221
	v_cndmask_b32_e64 v64, -v64, v64, s[40:41]
	v_add_f32_e32 v57, v64, v57
	v_and_b32_e32 v59, 0xffff0000, v220
	v_cndmask_b32_e64 v59, -v59, v59, s[40:41]
	v_add_f32_e32 v58, v59, v58
	v_lshlrev_b32_e32 v59, 16, v225
	v_cndmask_b32_e64 v51, v51, v59, s[42:43]
	v_cvt_pk_bf16_f32 v60, v51, v52
	v_cvt_pk_bf16_f32 v61, v53, v54
	v_cvt_pk_bf16_f32 v62, v55, v56
	v_cvt_pk_bf16_f32 v63, v57, v58
	global_store_dwordx4 v44, v[60:63], s[36:37]
	s_waitcnt vmcnt(25)
	v_lshlrev_b32_e32 v51, 16, v226
	v_and_b32_e32 v52, 0xffff0000, v226
	v_lshlrev_b32_e32 v53, 16, v227
	v_and_b32_e32 v54, 0xffff0000, v227
	v_lshlrev_b32_e32 v55, 16, v228
	v_and_b32_e32 v56, 0xffff0000, v228
	v_lshlrev_b32_e32 v57, 16, v229
	v_and_b32_e32 v58, 0xffff0000, v229
	v_lshlrev_b32_e32 v59, 16, v234
	v_cndmask_b32_e64 v59, v59, 0, s[34:35]
	v_cndmask_b32_e64 v59, -v59, v59, s[40:41]
	v_add_f32_e32 v51, v59, v51
	v_and_b32_e32 v59, 0xffff0000, v233
	v_cndmask_b32_e64 v59, -v59, v59, s[40:41]
	v_add_f32_e32 v52, v59, v52
	v_lshlrev_b32_e32 v64, 16, v233
	v_cndmask_b32_e64 v64, -v64, v64, s[40:41]
	v_add_f32_e32 v53, v64, v53
	v_and_b32_e32 v59, 0xffff0000, v232
	v_cndmask_b32_e64 v59, -v59, v59, s[40:41]
	v_add_f32_e32 v54, v59, v54
	v_lshlrev_b32_e32 v64, 16, v232
	v_cndmask_b32_e64 v64, -v64, v64, s[40:41]
	v_add_f32_e32 v55, v64, v55
	v_and_b32_e32 v59, 0xffff0000, v231
	v_cndmask_b32_e64 v59, -v59, v59, s[40:41]
	v_add_f32_e32 v56, v59, v56
	v_lshlrev_b32_e32 v64, 16, v231
	v_cndmask_b32_e64 v64, -v64, v64, s[40:41]
	v_add_f32_e32 v57, v64, v57
	v_and_b32_e32 v59, 0xffff0000, v230
	v_cndmask_b32_e64 v59, -v59, v59, s[40:41]
	v_add_f32_e32 v58, v59, v58
	v_lshlrev_b32_e32 v59, 16, v235
	v_cndmask_b32_e64 v51, v51, v59, s[42:43]
	v_cvt_pk_bf16_f32 v60, v51, v52
	v_cvt_pk_bf16_f32 v61, v53, v54
	v_cvt_pk_bf16_f32 v62, v55, v56
	v_cvt_pk_bf16_f32 v63, v57, v58
	s_add_u32 s54, s36, 0x200000
	s_addc_u32 s55, s37, 0
	global_store_dwordx4 v44, v[60:63], s[54:55]
	s_waitcnt vmcnt(22)
; DI unsigned cvtpk(float lo, float hi) { f32x2 v = {lo, hi}; bf16x2_t b = __builtin_convertvector(v, bf16x2_t); return __builtin_bit_cast(unsigned, b); }
; DI float bflo(unsigned u) { return __uint_as_float(u << 16); }
; DI float bfhi(unsigned u) { return __uint_as_float(u & 0xffff0000u); }
; DI void phase_feat_c(KP p, int l) {
;     ...
;       const u32x4 fw = *(const u32x4*)(fr + f0), ml = *(const u32x4*)(fr + mi - 8);
;       const float m0v = bflo((unsigned)fr[(mi < 4096) ? mi : 4095]);
;       const float f[8] = {bflo(fw.x), bfhi(fw.x), bflo(fw.y), bfhi(fw.y), bflo(fw.z), bfhi(fw.z), bflo(fw.w), bfhi(fw.w)};
;       const float mr[8] = {m0v, bfhi(ml.w), bflo(ml.w), bfhi(ml.z), bflo(ml.z), bfhi(ml.y), bflo(ml.y), bfhi(ml.x)};
;       float v[8];
; #pragma unroll
;       for (int e = 0; e < 8; ++e) {
;         const int k = k8 + e;
;         if (k < 1024) v[e] = f[e] + ((k == 0) ? 0.f : mr[e]);
;         else if (k == 1024) v[e] = bflo((unsigned)fr[1024]);
;         else v[e] = f[e] - mr[e];
;       }
;       u32x4 o = {cvtpk(v[0], v[1]), cvtpk(v[2], v[3]), cvtpk(v[4], v[5]), cvtpk(v[6], v[7])};
;       *(u32x4*)(FTF + (size_t)row * 2048 + k8) = o;
	v_lshlrev_b32_e32 v51, 16, v236
	v_and_b32_e32 v52, 0xffff0000, v236
	v_lshlrev_b32_e32 v53, 16, v237
	v_and_b32_e32 v54, 0xffff0000, v237
	v_lshlrev_b32_e32 v55, 16, v238
	v_and_b32_e32 v56, 0xffff0000, v238
	v_lshlrev_b32_e32 v57, 16, v239
	v_and_b32_e32 v58, 0xffff0000, v239
	v_lshlrev_b32_e32 v59, 16, v244
	v_cndmask_b32_e64 v59, v59, 0, s[34:35]
	v_cndmask_b32_e64 v59, -v59, v59, s[40:41]
	v_add_f32_e32 v51, v59, v51
	v_and_b32_e32 v59, 0xffff0000, v243
	v_cndmask_b32_e64 v59, -v59, v59, s[40:41]
	v_add_f32_e32 v52, v59, v52
	v_lshlrev_b32_e32 v64, 16, v243
	v_cndmask_b32_e64 v64, -v64, v64, s[40:41]
	v_add_f32_e32 v53, v64, v53
	v_and_b32_e32 v59, 0xffff0000, v242
	v_cndmask_b32_e64 v59, -v59, v59, s[40:41]
	v_add_f32_e32 v54, v59, v54
	v_lshlrev_b32_e32 v64, 16, v242
	v_cndmask_b32_e64 v64, -v64, v64, s[40:41]
	v_add_f32_e32 v55, v64, v55
	v_and_b32_e32 v59, 0xffff0000, v241
	v_cndmask_b32_e64 v59, -v59, v59, s[40:41]
	v_add_f32_e32 v56, v59, v56
	v_lshlrev_b32_e32 v64, 16, v241
	v_cndmask_b32_e64 v64, -v64, v64, s[40:41]
	v_add_f32_e32 v57, v64, v57
	v_and_b32_e32 v59, 0xffff0000, v240
	v_cndmask_b32_e64 v59, -v59, v59, s[40:41]
	v_add_f32_e32 v58, v59, v58
	v_lshlrev_b32_e32 v59, 16, v245
	v_cndmask_b32_e64 v51, v51, v59, s[42:43]
	v_cvt_pk_bf16_f32 v60, v51, v52
	v_cvt_pk_bf16_f32 v61, v53, v54
	v_cvt_pk_bf16_f32 v62, v55, v56
	v_cvt_pk_bf16_f32 v63, v57, v58
	s_add_u32 s54, s36, 0x400000
	s_addc_u32 s55, s37, 0
	global_store_dwordx4 v44, v[60:63], s[54:55]
	s_waitcnt vmcnt(19)
	v_lshlrev_b32_e32 v51, 16, v128
	v_and_b32_e32 v52, 0xffff0000, v128
	v_lshlrev_b32_e32 v53, 16, v129
	v_and_b32_e32 v54, 0xffff0000, v129
	v_lshlrev_b32_e32 v55, 16, v130
	v_and_b32_e32 v56, 0xffff0000, v130
	v_lshlrev_b32_e32 v57, 16, v131
	v_and_b32_e32 v58, 0xffff0000, v131
	v_lshlrev_b32_e32 v59, 16, v136
	v_cndmask_b32_e64 v59, v59, 0, s[34:35]
	v_cndmask_b32_e64 v59, -v59, v59, s[40:41]
	v_add_f32_e32 v51, v59, v51
	v_and_b32_e32 v59, 0xffff0000, v135
	v_cndmask_b32_e64 v59, -v59, v59, s[40:41]
	v_add_f32_e32 v52, v59, v52
	v_lshlrev_b32_e32 v64, 16, v135
	v_cndmask_b32_e64 v64, -v64, v64, s[40:41]
	v_add_f32_e32 v53, v64, v53
	v_and_b32_e32 v59, 0xffff0000, v134
	v_cndmask_b32_e64 v59, -v59, v59, s[40:41]
	v_add_f32_e32 v54, v59, v54
	v_lshlrev_b32_e32 v64, 16, v134
	v_cndmask_b32_e64 v64, -v64, v64, s[40:41]
	v_add_f32_e32 v55, v64, v55
	v_and_b32_e32 v59, 0xffff0000, v133
	v_cndmask_b32_e64 v59, -v59, v59, s[40:41]
	v_add_f32_e32 v56, v59, v56
	v_lshlrev_b32_e32 v64, 16, v133
	v_cndmask_b32_e64 v64, -v64, v64, s[40:41]
	v_add_f32_e32 v57, v64, v57
	v_and_b32_e32 v59, 0xffff0000, v132
	v_cndmask_b32_e64 v59, -v59, v59, s[40:41]
	v_add_f32_e32 v58, v59, v58
	v_lshlrev_b32_e32 v59, 16, v137
	v_cndmask_b32_e64 v51, v51, v59, s[42:43]
	v_cvt_pk_bf16_f32 v60, v51, v52
	v_cvt_pk_bf16_f32 v61, v53, v54
	v_cvt_pk_bf16_f32 v62, v55, v56
	v_cvt_pk_bf16_f32 v63, v57, v58
	s_add_u32 s54, s36, 0x600000
	s_addc_u32 s55, s37, 0
	global_store_dwordx4 v44, v[60:63], s[54:55]
	s_waitcnt vmcnt(16)
	v_lshlrev_b32_e32 v51, 16, v138
	v_and_b32_e32 v52, 0xffff0000, v138
	v_lshlrev_b32_e32 v53, 16, v139
	v_and_b32_e32 v54, 0xffff0000, v139
	v_lshlrev_b32_e32 v55, 16, v140
	v_and_b32_e32 v56, 0xffff0000, v140
	v_lshlrev_b32_e32 v57, 16, v141
	v_and_b32_e32 v58, 0xffff0000, v141
	v_lshlrev_b32_e32 v59, 16, v146
	v_cndmask_b32_e64 v59, v59, 0, s[34:35]
	v_cndmask_b32_e64 v59, -v59, v59, s[40:41]
	v_add_f32_e32 v51, v59, v51
	v_and_b32_e32 v59, 0xffff0000, v145
	v_cndmask_b32_e64 v59, -v59, v59, s[40:41]
	v_add_f32_e32 v52, v59, v52
	v_lshlrev_b32_e32 v64, 16, v145
	v_cndmask_b32_e64 v64, -v64, v64, s[40:41]
	v_add_f32_e32 v53, v64, v53
	v_and_b32_e32 v59, 0xffff0000, v144
	v_cndmask_b32_e64 v59, -v59, v59, s[40:41]
	v_add_f32_e32 v54, v59, v54
	v_lshlrev_b32_e32 v64, 16, v144
	v_cndmask_b32_e64 v64, -v64, v64, s[40:41]
	v_add_f32_e32 v55, v64, v55
	v_and_b32_e32 v59, 0xffff0000, v143
	v_cndmask_b32_e64 v59, -v59, v59, s[40:41]
	v_add_f32_e32 v56, v59, v56
	v_lshlrev_b32_e32 v64, 16, v143
	v_cndmask_b32_e64 v64, -v64, v64, s[40:41]
	v_add_f32_e32 v57, v64, v57
	v_and_b32_e32 v59, 0xffff0000, v142
	v_cndmask_b32_e64 v59, -v59, v59, s[40:41]
	v_add_f32_e32 v58, v59, v58
	v_lshlrev_b32_e32 v59, 16, v147
	v_cndmask_b32_e64 v51, v51, v59, s[42:43]
	v_cvt_pk_bf16_f32 v60, v51, v52
	v_cvt_pk_bf16_f32 v61, v53, v54
	v_cvt_pk_bf16_f32 v62, v55, v56
	v_cvt_pk_bf16_f32 v63, v57, v58
	s_add_u32 s54, s36, 0x800000
	s_addc_u32 s55, s37, 0
	global_store_dwordx4 v44, v[60:63], s[54:55]
	s_waitcnt vmcnt(13)
; DI unsigned cvtpk(float lo, float hi) { f32x2 v = {lo, hi}; bf16x2_t b = __builtin_convertvector(v, bf16x2_t); return __builtin_bit_cast(unsigned, b); }
; DI float bflo(unsigned u) { return __uint_as_float(u << 16); }
; DI float bfhi(unsigned u) { return __uint_as_float(u & 0xffff0000u); }
; DI void phase_feat_c(KP p, int l) {
;     ...
;       const u32x4 fw = *(const u32x4*)(fr + f0), ml = *(const u32x4*)(fr + mi - 8);
;       const float m0v = bflo((unsigned)fr[(mi < 4096) ? mi : 4095]);
;       const float f[8] = {bflo(fw.x), bfhi(fw.x), bflo(fw.y), bfhi(fw.y), bflo(fw.z), bfhi(fw.z), bflo(fw.w), bfhi(fw.w)};
;       const float mr[8] = {m0v, bfhi(ml.w), bflo(ml.w), bfhi(ml.z), bflo(ml.z), bfhi(ml.y), bflo(ml.y), bfhi(ml.x)};
;       float v[8];
; #pragma unroll
;       for (int e = 0; e < 8; ++e) {
;         const int k = k8 + e;
;         if (k < 1024) v[e] = f[e] + ((k == 0) ? 0.f : mr[e]);
;         else if (k == 1024) v[e] = bflo((unsigned)fr[1024]);
;         else v[e] = f[e] - mr[e];
;       }
;       u32x4 o = {cvtpk(v[0], v[1]), cvtpk(v[2], v[3]), cvtpk(v[4], v[5]), cvtpk(v[6], v[7])};
;       *(u32x4*)(FTF + (size_t)row * 2048 + k8) = o;
	v_lshlrev_b32_e32 v51, 16, v148
	v_and_b32_e32 v52, 0xffff0000, v148
	v_lshlrev_b32_e32 v53, 16, v149
	v_and_b32_e32 v54, 0xffff0000, v149
	v_lshlrev_b32_e32 v55, 16, v150
	v_and_b32_e32 v56, 0xffff0000, v150
	v_lshlrev_b32_e32 v57, 16, v151
	v_and_b32_e32 v58, 0xffff0000, v151
	v_lshlrev_b32_e32 v59, 16, v156
	v_cndmask_b32_e64 v59, v59, 0, s[34:35]
	v_cndmask_b32_e64 v59, -v59, v59, s[40:41]
	v_add_f32_e32 v51, v59, v51
	v_and_b32_e32 v59, 0xffff0000, v155
	v_cndmask_b32_e64 v59, -v59, v59, s[40:41]
	v_add_f32_e32 v52, v59, v52
	v_lshlrev_b32_e32 v64, 16, v155
	v_cndmask_b32_e64 v64, -v64, v64, s[40:41]
	v_add_f32_e32 v53, v64, v53
	v_and_b32_e32 v59, 0xffff0000, v154
	v_cndmask_b32_e64 v59, -v59, v59, s[40:41]
	v_add_f32_e32 v54, v59, v54
	v_lshlrev_b32_e32 v64, 16, v154
	v_cndmask_b32_e64 v64, -v64, v64, s[40:41]
	v_add_f32_e32 v55, v64, v55
	v_and_b32_e32 v59, 0xffff0000, v153
	v_cndmask_b32_e64 v59, -v59, v59, s[40:41]
	v_add_f32_e32 v56, v59, v56
	v_lshlrev_b32_e32 v64, 16, v153
	v_cndmask_b32_e64 v64, -v64, v64, s[40:41]
	v_add_f32_e32 v57, v64, v57
	v_and_b32_e32 v59, 0xffff0000, v152
	v_cndmask_b32_e64 v59, -v59, v59, s[40:41]
	v_add_f32_e32 v58, v59, v58
	v_lshlrev_b32_e32 v59, 16, v157
	v_cndmask_b32_e64 v51, v51, v59, s[42:43]
	v_cvt_pk_bf16_f32 v60, v51, v52
	v_cvt_pk_bf16_f32 v61, v53, v54
	v_cvt_pk_bf16_f32 v62, v55, v56
	v_cvt_pk_bf16_f32 v63, v57, v58
	s_add_u32 s54, s36, 0xa00000
	s_addc_u32 s55, s37, 0
	global_store_dwordx4 v44, v[60:63], s[54:55]
	s_waitcnt vmcnt(10)
	v_lshlrev_b32_e32 v51, 16, v82
	v_and_b32_e32 v52, 0xffff0000, v82
	v_lshlrev_b32_e32 v53, 16, v83
	v_and_b32_e32 v54, 0xffff0000, v83
	v_lshlrev_b32_e32 v55, 16, v84
	v_and_b32_e32 v56, 0xffff0000, v84
	v_lshlrev_b32_e32 v57, 16, v85
	v_and_b32_e32 v58, 0xffff0000, v85
	v_lshlrev_b32_e32 v59, 16, v90
	v_cndmask_b32_e64 v59, v59, 0, s[34:35]
	v_cndmask_b32_e64 v59, -v59, v59, s[40:41]
	v_add_f32_e32 v51, v59, v51
	v_and_b32_e32 v59, 0xffff0000, v89
	v_cndmask_b32_e64 v59, -v59, v59, s[40:41]
	v_add_f32_e32 v52, v59, v52
	v_lshlrev_b32_e32 v64, 16, v89
	v_cndmask_b32_e64 v64, -v64, v64, s[40:41]
	v_add_f32_e32 v53, v64, v53
	v_and_b32_e32 v59, 0xffff0000, v88
	v_cndmask_b32_e64 v59, -v59, v59, s[40:41]
	v_add_f32_e32 v54, v59, v54
	v_lshlrev_b32_e32 v64, 16, v88
	v_cndmask_b32_e64 v64, -v64, v64, s[40:41]
	v_add_f32_e32 v55, v64, v55
	v_and_b32_e32 v59, 0xffff0000, v87
	v_cndmask_b32_e64 v59, -v59, v59, s[40:41]
	v_add_f32_e32 v56, v59, v56
	v_lshlrev_b32_e32 v64, 16, v87
	v_cndmask_b32_e64 v64, -v64, v64, s[40:41]
	v_add_f32_e32 v57, v64, v57
	v_and_b32_e32 v59, 0xffff0000, v86
	v_cndmask_b32_e64 v59, -v59, v59, s[40:41]
	v_add_f32_e32 v58, v59, v58
	v_lshlrev_b32_e32 v59, 16, v91
	v_cndmask_b32_e64 v51, v51, v59, s[42:43]
	v_cvt_pk_bf16_f32 v60, v51, v52
	v_cvt_pk_bf16_f32 v61, v53, v54
	v_cvt_pk_bf16_f32 v62, v55, v56
	v_cvt_pk_bf16_f32 v63, v57, v58
	s_add_u32 s54, s36, 0xc00000
	s_addc_u32 s55, s37, 0
	global_store_dwordx4 v44, v[60:63], s[54:55]
	s_waitcnt vmcnt(7)
	v_lshlrev_b32_e32 v51, 16, v92
	v_and_b32_e32 v52, 0xffff0000, v92
	v_lshlrev_b32_e32 v53, 16, v93
	v_and_b32_e32 v54, 0xffff0000, v93
	v_lshlrev_b32_e32 v55, 16, v94
	v_and_b32_e32 v56, 0xffff0000, v94
	v_lshlrev_b32_e32 v57, 16, v95
	v_and_b32_e32 v58, 0xffff0000, v95
	v_lshlrev_b32_e32 v59, 16, v100
	v_cndmask_b32_e64 v59, v59, 0, s[34:35]
	v_cndmask_b32_e64 v59, -v59, v59, s[40:41]
	v_add_f32_e32 v51, v59, v51
	v_and_b32_e32 v59, 0xffff0000, v99
	v_cndmask_b32_e64 v59, -v59, v59, s[40:41]
	v_add_f32_e32 v52, v59, v52
	v_lshlrev_b32_e32 v64, 16, v99
	v_cndmask_b32_e64 v64, -v64, v64, s[40:41]
	v_add_f32_e32 v53, v64, v53
	v_and_b32_e32 v59, 0xffff0000, v98
	v_cndmask_b32_e64 v59, -v59, v59, s[40:41]
	v_add_f32_e32 v54, v59, v54
	v_lshlrev_b32_e32 v64, 16, v98
	v_cndmask_b32_e64 v64, -v64, v64, s[40:41]
	v_add_f32_e32 v55, v64, v55
	v_and_b32_e32 v59, 0xffff0000, v97
	v_cndmask_b32_e64 v59, -v59, v59, s[40:41]
	v_add_f32_e32 v56, v59, v56
	v_lshlrev_b32_e32 v64, 16, v97
	v_cndmask_b32_e64 v64, -v64, v64, s[40:41]
	v_add_f32_e32 v57, v64, v57
	v_and_b32_e32 v59, 0xffff0000, v96
	v_cndmask_b32_e64 v59, -v59, v59, s[40:41]
	v_add_f32_e32 v58, v59, v58
	v_lshlrev_b32_e32 v59, 16, v101
	v_cndmask_b32_e64 v51, v51, v59, s[42:43]
	v_cvt_pk_bf16_f32 v60, v51, v52
	v_cvt_pk_bf16_f32 v61, v53, v54
	v_cvt_pk_bf16_f32 v62, v55, v56
	v_cvt_pk_bf16_f32 v63, v57, v58
	s_add_u32 s54, s36, 0xe00000
	s_addc_u32 s55, s37, 0
	global_store_dwordx4 v44, v[60:63], s[54:55]
